# removed the redundant s_nop 0 in front of the first DMA of K-loop segment P8 (its m0 write already sits in the preceding MFMA block)
# baseline (speedup 1.0000x reference)
.LBB0_522:
	s_waitcnt lgkmcnt(0)
	ds_read_b128 v[128:131], v140
	ds_read_b128 v[132:135], v140 offset:1024
	ds_read_b128 v[136:139], v140 offset:2048
	ds_read_b128 v[140:143], v140 offset:3072
	ds_read_b128 v[144:147], v240
	ds_read_b128 v[148:151], v240 offset:1024
	ds_read_b128 v[152:155], v240 offset:2048
	ds_read_b128 v[156:159], v240 offset:3072
	ds_read_b128 v[160:163], v240 offset:4096
	ds_read_b128 v[164:167], v240 offset:5120
	ds_read_b128 v[168:171], v240 offset:6144
	ds_read_b128 v[172:175], v240 offset:7168
	global_load_lds_dwordx4 v[176:177], off
	s_add_i32 m0, s93, 0xe000
	s_nop 0
	global_load_lds_dwordx4 v[178:179], off
	s_waitcnt lgkmcnt(8)
	s_barrier
	s_waitcnt lgkmcnt(0)
	v_mfma_f32_16x16x32_bf16 v[124:127], v[128:131], v[144:147], v[124:127]
	s_add_i32 vcc_lo, s74, 2
	v_mfma_f32_16x16x32_bf16 v[120:123], v[136:139], v[144:147], v[120:123]
	s_add_u32 s76, s72, 0x80
	v_mfma_f32_16x16x32_bf16 v[116:119], v[128:131], v[152:155], v[116:119]
	s_addc_u32 s75, s73, 0
	v_mfma_f32_16x16x32_bf16 v[112:115], v[136:139], v[152:155], v[112:115]
	s_cmp_eq_u32 s50, s74
	v_mfma_f32_16x16x32_bf16 v[100:103], v[128:131], v[160:163], v[100:103]
	s_cselect_b32 s74, s68, s76
	v_mfma_f32_16x16x32_bf16 v[96:99], v[136:139], v[160:163], v[96:99]
	s_cselect_b32 s75, s69, s75
	v_mfma_f32_16x16x32_bf16 v[84:87], v[128:131], v[168:171], v[84:87]
	s_cselect_b32 s77, s71, s79
	v_mfma_f32_16x16x32_bf16 v[80:83], v[136:139], v[168:171], v[80:83]
	s_cselect_b32 s76, s70, s78
	v_mfma_f32_16x16x32_bf16 v[124:127], v[132:135], v[148:151], v[124:127]
	s_add_i32 s31, 0, 0x14000
	v_mfma_f32_16x16x32_bf16 v[120:123], v[140:143], v[148:151], v[120:123]
	s_add_i32 vcc_hi, vcc_hi, s87
	v_mfma_f32_16x16x32_bf16 v[116:119], v[132:135], v[156:159], v[116:119]
	v_add_u32_e32 v188, s31, v237
	v_mfma_f32_16x16x32_bf16 v[112:115], v[140:143], v[156:159], v[112:115]
	v_lshl_add_u64 v[210:211], s[76:77], 0, v[196:197]
	v_mfma_f32_16x16x32_bf16 v[100:103], v[132:135], v[164:167], v[100:103]
	s_mov_b32 m0, vcc_hi
	v_mfma_f32_16x16x32_bf16 v[96:99], v[140:143], v[164:167], v[96:99]
	v_mfma_f32_16x16x32_bf16 v[84:87], v[132:135], v[172:175], v[84:87]
	v_mfma_f32_16x16x32_bf16 v[80:83], v[140:143], v[172:175], v[80:83]
	s_barrier
	ds_read_b128 v[176:179], v188
	ds_read_b128 v[180:183], v188 offset:1024
	ds_read_b128 v[184:187], v188 offset:2048
	ds_read_b128 v[188:191], v188 offset:3072
	global_load_lds_dwordx4 v[210:211], off
	v_lshl_add_u64 v[212:213], s[76:77], 0, v[200:201]
	s_add_i32 m0, vcc_hi, 0x2000
	s_nop 0
	global_load_lds_dwordx4 v[212:213], off
	s_barrier
	s_waitcnt lgkmcnt(0)
	v_mfma_f32_16x16x32_bf16 v[108:111], v[176:179], v[144:147], v[108:111]
	v_mfma_f32_16x16x32_bf16 v[104:107], v[184:187], v[144:147], v[104:107]
	v_mfma_f32_16x16x32_bf16 v[92:95], v[176:179], v[152:155], v[92:95]
	v_mfma_f32_16x16x32_bf16 v[88:91], v[184:187], v[152:155], v[88:91]
	v_mfma_f32_16x16x32_bf16 v[76:79], v[176:179], v[160:163], v[76:79]
	v_mfma_f32_16x16x32_bf16 v[72:75], v[184:187], v[160:163], v[72:75]
	v_mfma_f32_16x16x32_bf16 v[68:71], v[176:179], v[168:171], v[68:71]
	v_mfma_f32_16x16x32_bf16 v[64:67], v[184:187], v[168:171], v[64:67]
	v_mfma_f32_16x16x32_bf16 v[108:111], v[180:183], v[148:151], v[108:111]
	s_mov_b32 m0, s93
	v_mfma_f32_16x16x32_bf16 v[104:107], v[188:191], v[148:151], v[104:107]
	v_lshl_add_u64 v[214:215], s[74:75], 0, v[194:195]
	v_mfma_f32_16x16x32_bf16 v[92:95], v[180:183], v[156:159], v[92:95]
	v_mfma_f32_16x16x32_bf16 v[88:91], v[188:191], v[156:159], v[88:91]
	v_mfma_f32_16x16x32_bf16 v[76:79], v[180:183], v[164:167], v[76:79]
	v_mfma_f32_16x16x32_bf16 v[72:75], v[188:191], v[164:167], v[72:75]
	v_mfma_f32_16x16x32_bf16 v[68:71], v[180:183], v[172:175], v[68:71]
	v_mfma_f32_16x16x32_bf16 v[64:67], v[188:191], v[172:175], v[64:67]
	s_barrier
	ds_read_b128 v[144:147], v240 offset:16384
	ds_read_b128 v[148:151], v240 offset:17408
	ds_read_b128 v[152:155], v240 offset:18432
	ds_read_b128 v[156:159], v240 offset:19456
	ds_read_b128 v[160:163], v240 offset:20480
	ds_read_b128 v[164:167], v240 offset:21504
	ds_read_b128 v[168:171], v240 offset:22528
	ds_read_b128 v[172:175], v240 offset:23552
	global_load_lds_dwordx4 v[214:215], off
	v_lshl_add_u64 v[216:217], s[74:75], 0, v[198:199]
	s_mov_b32 m0, s54
	s_nop 0
	global_load_lds_dwordx4 v[216:217], off
	s_barrier
	s_waitcnt lgkmcnt(0)
	v_mfma_f32_16x16x32_bf16 v[60:63], v[128:131], v[144:147], v[60:63]
	v_mfma_f32_16x16x32_bf16 v[56:59], v[136:139], v[144:147], v[56:59]
	v_mfma_f32_16x16x32_bf16 v[52:55], v[128:131], v[152:155], v[52:55]
	v_mfma_f32_16x16x32_bf16 v[48:51], v[136:139], v[152:155], v[48:51]
	v_mfma_f32_16x16x32_bf16 v[36:39], v[128:131], v[160:163], v[36:39]
	v_mfma_f32_16x16x32_bf16 v[32:35], v[136:139], v[160:163], v[32:35]
	v_mfma_f32_16x16x32_bf16 v[20:23], v[128:131], v[168:171], v[20:23]
	v_mfma_f32_16x16x32_bf16 v[16:19], v[136:139], v[168:171], v[16:19]
	v_mfma_f32_16x16x32_bf16 v[60:63], v[132:135], v[148:151], v[60:63]
	s_add_u32 s76, s76, s20
	v_mfma_f32_16x16x32_bf16 v[56:59], v[140:143], v[148:151], v[56:59]
	s_addc_u32 s77, s77, 0
	v_mfma_f32_16x16x32_bf16 v[52:55], v[132:135], v[156:159], v[52:55]
	s_add_i32 s31, s31, s87
	v_mfma_f32_16x16x32_bf16 v[48:51], v[140:143], v[156:159], v[48:51]
	v_lshl_add_u64 v[218:219], s[76:77], 0, v[196:197]
	v_mfma_f32_16x16x32_bf16 v[36:39], v[132:135], v[164:167], v[36:39]
	s_mov_b32 m0, s31
	v_mfma_f32_16x16x32_bf16 v[32:35], v[140:143], v[164:167], v[32:35]
	v_lshl_add_u64 v[220:221], s[76:77], 0, v[200:201]
	v_mfma_f32_16x16x32_bf16 v[20:23], v[132:135], v[172:175], v[20:23]
	v_mfma_f32_16x16x32_bf16 v[16:19], v[140:143], v[172:175], v[16:19]
	s_barrier
	global_load_lds_dwordx4 v[218:219], off
	s_add_i32 m0, s31, 0x2000
	s_nop 0
	global_load_lds_dwordx4 v[220:221], off
	s_waitcnt vmcnt(6)
	s_barrier
	v_mfma_f32_16x16x32_bf16 v[44:47], v[176:179], v[144:147], v[44:47]
	v_mfma_f32_16x16x32_bf16 v[40:43], v[184:187], v[144:147], v[40:43]
	v_mfma_f32_16x16x32_bf16 v[28:31], v[176:179], v[152:155], v[28:31]
	v_mfma_f32_16x16x32_bf16 v[24:27], v[184:187], v[152:155], v[24:27]
	v_mfma_f32_16x16x32_bf16 v[12:15], v[176:179], v[160:163], v[12:15]
	v_mfma_f32_16x16x32_bf16 v[8:11], v[184:187], v[160:163], v[8:11]
	v_mfma_f32_16x16x32_bf16 v[4:7], v[176:179], v[168:171], v[4:7]
	v_mfma_f32_16x16x32_bf16 v[0:3], v[184:187], v[168:171], v[0:3]
	v_mfma_f32_16x16x32_bf16 v[44:47], v[180:183], v[148:151], v[44:47]
	s_add_i32 s31, 0, 0x18000
	v_mfma_f32_16x16x32_bf16 v[40:43], v[188:191], v[148:151], v[40:43]
	v_add_u32_e32 v140, s31, v237
	v_mfma_f32_16x16x32_bf16 v[28:31], v[180:183], v[156:159], v[28:31]
	s_add_u32 s74, s74, s20
	v_mfma_f32_16x16x32_bf16 v[24:27], v[188:191], v[156:159], v[24:27]
	s_addc_u32 s75, s75, 0
	v_mfma_f32_16x16x32_bf16 v[12:15], v[180:183], v[164:167], v[12:15]
	s_mov_b32 m0, s34
	v_mfma_f32_16x16x32_bf16 v[8:11], v[188:191], v[164:167], v[8:11]
	v_lshl_add_u64 v[176:177], s[74:75], 0, v[194:195]
	v_mfma_f32_16x16x32_bf16 v[4:7], v[180:183], v[172:175], v[4:7]
	v_lshl_add_u64 v[178:179], s[74:75], 0, v[198:199]
	v_mfma_f32_16x16x32_bf16 v[0:3], v[188:191], v[172:175], v[0:3]
	s_barrier
	ds_read_b128 v[128:131], v140
	ds_read_b128 v[132:135], v140 offset:1024
	ds_read_b128 v[136:139], v140 offset:2048
	ds_read_b128 v[140:143], v140 offset:3072
	ds_read_b128 v[144:147], v240 offset:32768
	ds_read_b128 v[148:151], v240 offset:33792
	ds_read_b128 v[152:155], v240 offset:34816
	ds_read_b128 v[156:159], v240 offset:35840
	ds_read_b128 v[160:163], v240 offset:36864
	ds_read_b128 v[164:167], v240 offset:37888
	ds_read_b128 v[168:171], v240 offset:38912
	ds_read_b128 v[172:175], v240 offset:39936
	global_load_lds_dwordx4 v[176:177], off
	s_mov_b32 m0, s35
	s_nop 0
	global_load_lds_dwordx4 v[178:179], off
	s_waitcnt lgkmcnt(8)
	s_barrier
	s_waitcnt lgkmcnt(0)
	v_mfma_f32_16x16x32_bf16 v[124:127], v[128:131], v[144:147], v[124:127]
	v_mfma_f32_16x16x32_bf16 v[120:123], v[136:139], v[144:147], v[120:123]
	v_mfma_f32_16x16x32_bf16 v[116:119], v[128:131], v[152:155], v[116:119]
	v_mfma_f32_16x16x32_bf16 v[112:115], v[136:139], v[152:155], v[112:115]
	v_mfma_f32_16x16x32_bf16 v[100:103], v[128:131], v[160:163], v[100:103]
	v_mfma_f32_16x16x32_bf16 v[96:99], v[136:139], v[160:163], v[96:99]
	v_mfma_f32_16x16x32_bf16 v[84:87], v[128:131], v[168:171], v[84:87]
	v_mfma_f32_16x16x32_bf16 v[80:83], v[136:139], v[168:171], v[80:83]
	v_mfma_f32_16x16x32_bf16 v[124:127], v[132:135], v[148:151], v[124:127]
	s_add_i32 s74, 0, 0x1c000
	v_mfma_f32_16x16x32_bf16 v[120:123], v[140:143], v[148:151], v[120:123]
	s_add_i32 s31, s31, s87
	v_mfma_f32_16x16x32_bf16 v[116:119], v[132:135], v[156:159], v[116:119]
	v_add_u32_e32 v188, s74, v237
	v_mfma_f32_16x16x32_bf16 v[112:115], v[140:143], v[156:159], v[112:115]
	v_lshl_add_u64 v[210:211], v[210:211], 0, s[60:61]
	v_mfma_f32_16x16x32_bf16 v[100:103], v[132:135], v[164:167], v[100:103]
	s_mov_b32 m0, s31
	v_mfma_f32_16x16x32_bf16 v[96:99], v[140:143], v[164:167], v[96:99]
	v_mfma_f32_16x16x32_bf16 v[84:87], v[132:135], v[172:175], v[84:87]
	v_mfma_f32_16x16x32_bf16 v[80:83], v[140:143], v[172:175], v[80:83]
	s_barrier
	ds_read_b128 v[176:179], v188
	ds_read_b128 v[180:183], v188 offset:1024
	ds_read_b128 v[184:187], v188 offset:2048
	ds_read_b128 v[188:191], v188 offset:3072
	global_load_lds_dwordx4 v[210:211], off
	v_lshl_add_u64 v[210:211], v[212:213], 0, s[60:61]
	s_add_i32 m0, s31, 0x2000
	s_nop 0
	global_load_lds_dwordx4 v[210:211], off
	s_barrier
	s_waitcnt lgkmcnt(0)
	v_mfma_f32_16x16x32_bf16 v[108:111], v[176:179], v[144:147], v[108:111]
	v_mfma_f32_16x16x32_bf16 v[104:107], v[184:187], v[144:147], v[104:107]
	v_mfma_f32_16x16x32_bf16 v[92:95], v[176:179], v[152:155], v[92:95]
	v_mfma_f32_16x16x32_bf16 v[88:91], v[184:187], v[152:155], v[88:91]
	v_mfma_f32_16x16x32_bf16 v[76:79], v[176:179], v[160:163], v[76:79]
	v_mfma_f32_16x16x32_bf16 v[72:75], v[184:187], v[160:163], v[72:75]
	v_mfma_f32_16x16x32_bf16 v[68:71], v[176:179], v[168:171], v[68:71]
	v_mfma_f32_16x16x32_bf16 v[64:67], v[184:187], v[168:171], v[64:67]
	v_mfma_f32_16x16x32_bf16 v[108:111], v[180:183], v[148:151], v[108:111]
	s_mov_b32 m0, s97
	v_mfma_f32_16x16x32_bf16 v[104:107], v[188:191], v[148:151], v[104:107]
	v_lshl_add_u64 v[210:211], v[214:215], 0, s[60:61]
	v_mfma_f32_16x16x32_bf16 v[92:95], v[180:183], v[156:159], v[92:95]
	v_mfma_f32_16x16x32_bf16 v[88:91], v[188:191], v[156:159], v[88:91]
	v_mfma_f32_16x16x32_bf16 v[76:79], v[180:183], v[164:167], v[76:79]
	v_mfma_f32_16x16x32_bf16 v[72:75], v[188:191], v[164:167], v[72:75]
	v_mfma_f32_16x16x32_bf16 v[68:71], v[180:183], v[172:175], v[68:71]
	v_mfma_f32_16x16x32_bf16 v[64:67], v[188:191], v[172:175], v[64:67]
	s_barrier
	ds_read_b128 v[144:147], v240 offset:49152
	ds_read_b128 v[148:151], v240 offset:50176
	ds_read_b128 v[152:155], v240 offset:51200
	ds_read_b128 v[156:159], v240 offset:52224
	ds_read_b128 v[160:163], v240 offset:53248
	ds_read_b128 v[164:167], v240 offset:54272
	ds_read_b128 v[168:171], v240 offset:55296
	ds_read_b128 v[172:175], v240 offset:56320
	global_load_lds_dwordx4 v[210:211], off
	v_lshl_add_u64 v[210:211], v[216:217], 0, s[60:61]
	s_mov_b32 m0, s36
	s_nop 0
	global_load_lds_dwordx4 v[210:211], off
	s_barrier
	s_waitcnt lgkmcnt(0)
	v_mfma_f32_16x16x32_bf16 v[60:63], v[128:131], v[144:147], v[60:63]
	v_mfma_f32_16x16x32_bf16 v[56:59], v[136:139], v[144:147], v[56:59]
	v_mfma_f32_16x16x32_bf16 v[52:55], v[128:131], v[152:155], v[52:55]
	v_mfma_f32_16x16x32_bf16 v[48:51], v[136:139], v[152:155], v[48:51]
	v_mfma_f32_16x16x32_bf16 v[36:39], v[128:131], v[160:163], v[36:39]
	v_mfma_f32_16x16x32_bf16 v[32:35], v[136:139], v[160:163], v[32:35]
	v_mfma_f32_16x16x32_bf16 v[20:23], v[128:131], v[168:171], v[20:23]
	v_mfma_f32_16x16x32_bf16 v[16:19], v[136:139], v[168:171], v[16:19]
	v_mfma_f32_16x16x32_bf16 v[60:63], v[132:135], v[148:151], v[60:63]
	s_add_i32 s31, s74, s87
	v_mfma_f32_16x16x32_bf16 v[56:59], v[140:143], v[148:151], v[56:59]
	v_lshl_add_u64 v[128:129], v[218:219], 0, s[60:61]
	v_mfma_f32_16x16x32_bf16 v[52:55], v[132:135], v[156:159], v[52:55]
	s_mov_b32 m0, s31
	v_mfma_f32_16x16x32_bf16 v[48:51], v[140:143], v[156:159], v[48:51]
	v_mfma_f32_16x16x32_bf16 v[36:39], v[132:135], v[164:167], v[36:39]
	v_mfma_f32_16x16x32_bf16 v[32:35], v[140:143], v[164:167], v[32:35]
	v_mfma_f32_16x16x32_bf16 v[20:23], v[132:135], v[172:175], v[20:23]
	v_mfma_f32_16x16x32_bf16 v[16:19], v[140:143], v[172:175], v[16:19]
	s_barrier
	global_load_lds_dwordx4 v[128:129], off
	v_lshl_add_u64 v[128:129], v[220:221], 0, s[60:61]
	s_add_i32 m0, s31, 0x2000
	s_nop 0
	global_load_lds_dwordx4 v[128:129], off
	s_waitcnt vmcnt(6)
	s_barrier
	v_mfma_f32_16x16x32_bf16 v[44:47], v[176:179], v[144:147], v[44:47]
	s_add_u32 s72, s72, 0x100
	v_mfma_f32_16x16x32_bf16 v[40:43], v[184:187], v[144:147], v[40:43]
	s_addc_u32 s73, s73, 0
	v_mfma_f32_16x16x32_bf16 v[28:31], v[176:179], v[152:155], v[28:31]
	s_add_u32 s78, s78, 0x100
	v_mfma_f32_16x16x32_bf16 v[24:27], v[184:187], v[152:155], v[24:27]
	s_addc_u32 s79, s79, 0
	v_mfma_f32_16x16x32_bf16 v[12:15], v[176:179], v[160:163], v[12:15]
	s_add_i32 vcc_hi, 0, 0x10000
	v_mfma_f32_16x16x32_bf16 v[8:11], v[184:187], v[160:163], v[8:11]
	v_add_u32_e32 v140, vcc_hi, v237
	v_mfma_f32_16x16x32_bf16 v[4:7], v[176:179], v[168:171], v[4:7]
	s_add_i32 m0, s93, 0xc000
	v_mfma_f32_16x16x32_bf16 v[0:3], v[184:187], v[168:171], v[0:3]
	s_cmp_ge_u32 vcc_lo, s30
	v_mfma_f32_16x16x32_bf16 v[44:47], v[180:183], v[148:151], v[44:47]
	s_mov_b32 s74, vcc_lo
	v_mfma_f32_16x16x32_bf16 v[40:43], v[188:191], v[148:151], v[40:43]
	v_mfma_f32_16x16x32_bf16 v[28:31], v[180:183], v[156:159], v[28:31]
	v_lshl_add_u64 v[176:177], s[72:73], 0, v[206:207]
	v_mfma_f32_16x16x32_bf16 v[24:27], v[188:191], v[156:159], v[24:27]
	v_mfma_f32_16x16x32_bf16 v[12:15], v[180:183], v[164:167], v[12:15]
	v_lshl_add_u64 v[178:179], s[72:73], 0, v[208:209]
	v_mfma_f32_16x16x32_bf16 v[8:11], v[188:191], v[164:167], v[8:11]
	v_mfma_f32_16x16x32_bf16 v[4:7], v[180:183], v[172:175], v[4:7]
	v_mfma_f32_16x16x32_bf16 v[0:3], v[188:191], v[172:175], v[0:3]
	s_barrier
	s_cbranch_scc0 .LBB0_522
	s_cmp_lt_i32 s91, 0
	s_mov_b64 s[72:73], -1
	s_cbranch_scc0 .LBB0_716
	s_lshl_b32 s78, s46, 8
	s_cmp_lt_i32 s81, 2
	s_cbranch_scc1 .LBB0_582
	s_cmp_lt_i32 s81, 3
	s_cbranch_scc1 .LBB0_579
	s_cmp_lg_u32 s81, 3
	s_cbranch_scc0 .LBB0_544
	v_lshl_or_b32 v128, s19, 7, v238
	v_ashrrev_i32_e32 v129, 31, v128
	v_lshl_add_u64 v[144:145], v[128:129], 1, s[24:25]
	v_and_b32_e32 v129, 64, v231
	v_xor_b32_e32 v128, 16, v231
	v_add_u32_e32 v129, 64, v129
	v_cmp_lt_i32_e32 vcc, v128, v129
	v_add_u32_e32 v146, s78, v202
	v_ashrrev_i32_e32 v147, 31, v146
	v_cndmask_b32_e32 v128, v231, v128, vcc
	v_lshlrev_b32_e32 v167, 2, v128
	v_xor_b32_e32 v128, 32, v231
	v_cmp_lt_i32_e32 vcc, v128, v129
	v_or_b32_e32 v156, 16, v146
	v_ashrrev_i32_e32 v157, 31, v156
	v_cndmask_b32_e32 v128, v231, v128, vcc
	v_lshlrev_b32_e32 v166, 2, v128
	v_lshlrev_b64 v[128:129], 12, v[146:147]
	v_lshl_add_u64 v[160:161], v[144:145], 0, v[128:129]
	global_load_dwordx4 v[140:143], v[160:161], off
	v_or_b32_e32 v152, 32, v146
	v_lshlrev_b64 v[128:129], 12, v[156:157]
	v_ashrrev_i32_e32 v153, 31, v152
	v_or_b32_e32 v148, 48, v146
	v_lshl_add_u64 v[158:159], v[144:145], 0, v[128:129]
	v_lshlrev_b64 v[128:129], 12, v[152:153]
	v_ashrrev_i32_e32 v149, 31, v148
	v_lshl_add_u64 v[154:155], v[144:145], 0, v[128:129]
	v_lshlrev_b64 v[128:129], 12, v[148:149]
	v_lshl_add_u64 v[150:151], v[144:145], 0, v[128:129]
	global_load_dwordx4 v[136:139], v[158:159], off
	global_load_dwordx4 v[132:135], v[154:155], off
	global_load_dwordx4 v[128:131], v[150:151], off
	v_mul_f32_e32 v163, 0xbfb8aa3b, v104
	v_exp_f32_e32 v163, v163
	v_mul_f32_e32 v162, 0xbfb8aa3b, v108
	v_exp_f32_e32 v162, v162
	v_add_f32_e32 v163, 1.0, v163
	v_rcp_f32_e32 v164, v163
	v_mul_f32_e32 v163, 0xbfb8aa3b, v109
	v_exp_f32_e32 v163, v163
	v_add_f32_e32 v162, 1.0, v162
	v_rcp_f32_e32 v162, v162
	v_add_f32_e32 v163, 1.0, v163
	v_rcp_f32_e32 v163, v163
	s_waitcnt vmcnt(0)
	v_lshlrev_b32_e32 v168, 16, v140
	v_and_b32_e32 v169, 0xffff0000, v140
	v_mul_f32_e32 v140, 0xbfb8aa3b, v105
	v_exp_f32_e32 v140, v140
	v_pk_fma_f32 v[162:163], v[162:163], v[124:125], v[168:169]
	v_lshlrev_b32_e32 v168, 16, v142
	v_and_b32_e32 v169, 0xffff0000, v142
	v_add_f32_e32 v140, 1.0, v140
	v_rcp_f32_e32 v165, v140
	v_mul_f32_e32 v140, 0xbfb8aa3b, v110
	v_exp_f32_e32 v140, v140
	v_mul_f32_e32 v142, 0xbfb8aa3b, v111
	v_pk_fma_f32 v[164:165], v[164:165], v[120:121], v[168:169]
	v_lshlrev_b32_e32 v170, 16, v141
	v_add_f32_e32 v140, 1.0, v140
	v_rcp_f32_e32 v168, v140
	v_mul_f32_e32 v140, 0xbfb8aa3b, v106
	v_and_b32_e32 v171, 0xffff0000, v141
	v_mul_f32_e32 v141, 0xbfb8aa3b, v107
	v_exp_f32_e32 v140, v140
	v_exp_f32_e32 v142, v142
	v_exp_f32_e32 v141, v141
	v_add_f32_e32 v140, 1.0, v140
	v_add_f32_e32 v142, 1.0, v142
	v_add_f32_e32 v141, 1.0, v141
	v_rcp_f32_e32 v140, v140
	v_rcp_f32_e32 v169, v142
	v_rcp_f32_e32 v141, v141
	v_lshlrev_b32_e32 v142, 16, v143
	v_and_b32_e32 v143, 0xffff0000, v143
	v_pk_fma_f32 v[168:169], v[168:169], v[126:127], v[170:171]
	v_pk_fma_f32 v[170:171], v[140:141], v[122:123], v[142:143]
	v_cvt_pk_bf16_f32 v140, v162, v163
	v_cvt_pk_bf16_f32 v141, v168, v169
	v_cvt_pk_bf16_f32 v142, v164, v165
	v_cvt_pk_bf16_f32 v143, v170, v171
	global_store_dwordx4 v[160:161], v[140:143], off
	v_pk_mul_f32 v[160:161], v[164:165], v[164:165]
	s_nop 0
	v_pk_mul_f32 v[140:141], v[162:163], v[162:163]
	v_pk_mul_f32 v[142:143], v[168:169], v[168:169]
	v_add_f32_e32 v140, v140, v141
	v_add_f32_e32 v142, v142, v143
	v_pk_mul_f32 v[162:163], v[170:171], v[170:171]
	v_add_f32_e32 v140, v140, v142
	v_add_f32_e32 v141, v160, v161
	v_add_f32_e32 v162, v162, v163
	v_add_f32_e32 v140, v141, v140
	v_add_f32_e32 v140, v162, v140
	v_mov_b32_e32 v141, v140
	s_nop 1
	v_permlane16_swap_b32_e32 v141, v140
	s_waitcnt lgkmcnt(0)
	v_add_f32_e32 v140, v140, v141
	v_mov_b32_e32 v141, v140
	s_nop 1
	v_permlane32_swap_b32_e32 v141, v140
	s_and_saveexec_b64 s[72:73], s[6:7]
	s_cbranch_execz .LBB0_529
	s_waitcnt lgkmcnt(0)
	v_add_f32_e32 v142, v140, v141
	s_lshl_b32 s74, s19, 2
	v_lshlrev_b64 v[140:141], 8, v[146:147]
	s_ashr_i32 s75, s74, 31
	v_lshl_add_u64 v[140:141], s[26:27], 0, v[140:141]
	v_lshl_add_u64 v[140:141], s[74:75], 2, v[140:141]
	s_lshl_b32 s50, s37, 2
	v_lshl_add_u64 v[140:141], v[140:141], 0, s[50:51]
	global_store_dword v[140:141], v142, off
